# MLA: trailing-half rendezvous moved to after the 16th S1 MFMA (end of first P.V chain)
# speedup vs baseline: 1.0554x; 1.0063x over previous
; #define HBAR() do { asm volatile("s_waitcnt lgkmcnt(0)" ::: "memory"); __builtin_amdgcn_s_barrier(); asm volatile("" ::: "memory"); } while (0)
; __device__ __forceinline__ void pv_both_kp(f32x16& o0, f32x16& o1, int vb, bf16x8 pa0, bf16x8 pa1, bf16x8 pa2, bf16x8 pa3) {
;     ...
;     asm volatile("s_waitcnt lgkmcnt(8)" ::: "memory"); __builtin_amdgcn_sched_barrier(0);
;     ...
;     o0 = __builtin_amdgcn_mfma_f32_32x32x16_bf16(pa0, PK(l0, h0), o0, 0, 0, 0);
;     o0 = __builtin_amdgcn_mfma_f32_32x32x16_bf16(pa1, PK(l1, h1), o0, 0, 0, 0);
;     o0 = __builtin_amdgcn_mfma_f32_32x32x16_bf16(pa2, PK(l2, h2), o0, 0, 0, 0);
;     o0 = __builtin_amdgcn_mfma_f32_32x32x16_bf16(pa3, PK(l3, h3), o0, 0, 0, 0);
;     asm volatile("s_waitcnt lgkmcnt(0)" ::: "memory"); __builtin_amdgcn_sched_barrier(0);
;     o1 = __builtin_amdgcn_mfma_f32_32x32x16_bf16(pa0, PK(m0, n0), o1, 0, 0, 0);
;     o1 = __builtin_amdgcn_mfma_f32_32x32x16_bf16(pa1, PK(m1, n1), o1, 0, 0, 0);
;     o1 = __builtin_amdgcn_mfma_f32_32x32x16_bf16(pa2, PK(m2, n2), o1, 0, 0, 0);
;     o1 = __builtin_amdgcn_mfma_f32_32x32x16_bf16(pa3, PK(m3, n3), o1, 0, 0, 0);
; __device__ __forceinline__ void mla_unit2(const Params& P, unsigned char* lds, int h, int rb, int grp, bool dry = false) {
;     ...
;         if (i > 0) { pv_both_kp(o[0], o[1], vb0 + A_VBUF, pa0, pa1, pa2, pa3); }
;         HBAR();
.LBB0_969:
	s_waitcnt lgkmcnt(3)
	v_mfma_f32_32x32x16_bf16 v[64:79], v[80:83], v[96:99], v[32:47]
	s_waitcnt lgkmcnt(1)
	v_mfma_f32_32x32x16_bf16 v[80:95], v[150:153], v[96:99], v[32:47]
	v_mfma_f32_32x32x16_bf16 v[64:79], v[146:149], v[100:103], v[64:79]
	ds_read_b128 v[146:149], v157 offset:64
	ds_read_b128 v[150:153], v157 offset:96
	s_waitcnt lgkmcnt(2)
	v_mfma_f32_32x32x16_bf16 v[80:95], v[168:171], v[100:103], v[80:95]
	s_waitcnt lgkmcnt(1)
	v_mfma_f32_32x32x16_bf16 v[64:79], v[146:149], v[104:107], v[64:79]
	ds_read_b128 v[146:149], v157 offset:6720
	ds_read_b128 v[168:171], v157 offset:6752
	s_waitcnt lgkmcnt(1)
	v_mfma_f32_32x32x16_bf16 v[80:95], v[146:149], v[104:107], v[80:95]
	v_mfma_f32_32x32x16_bf16 v[64:79], v[150:153], v[108:111], v[64:79]
	ds_read_b128 v[146:149], v157 offset:128
	ds_read_b128 v[150:153], v157 offset:160
	s_waitcnt lgkmcnt(2)
	v_mfma_f32_32x32x16_bf16 v[80:95], v[168:171], v[108:111], v[80:95]
	s_waitcnt lgkmcnt(1)
	v_mfma_f32_32x32x16_bf16 v[64:79], v[146:149], v[112:115], v[64:79]
	ds_read_b128 v[146:149], v157 offset:6784
	ds_read_b128 v[168:171], v157 offset:6816
	ds_read_b64_tr_b16 v[182:183], v204 offset:0
	ds_read_b64_tr_b16 v[184:185], v204 offset:0x100
	s_waitcnt lgkmcnt(1)
	v_mfma_f32_32x32x16_bf16 v[80:95], v[146:149], v[112:115], v[80:95]
	ds_read_b64_tr_b16 v[146:147], v204 offset:0x800
	ds_read_b64_tr_b16 v[148:149], v204 offset:0x900
	ds_read_b64_tr_b16 v[186:187], v204 offset:0x1000
	ds_read_b64_tr_b16 v[188:189], v204 offset:0x1100
	ds_read_b64_tr_b16 v[190:191], v204 offset:0x1800
	ds_read_b64_tr_b16 v[192:193], v204 offset:0x1900
	ds_read_b64_tr_b16 v[206:207], v204 offset:0x200
	ds_read_b64_tr_b16 v[208:209], v204 offset:0x300
	v_mfma_f32_32x32x16_bf16 v[64:79], v[150:153], v[116:119], v[64:79]
	ds_read_b64_tr_b16 v[150:151], v204 offset:0xa00
	ds_read_b64_tr_b16 v[152:153], v204 offset:0xb00
	ds_read_b64_tr_b16 v[210:211], v204 offset:0x1200
	ds_read_b64_tr_b16 v[212:213], v204 offset:0x1300
	ds_read_b64_tr_b16 v[214:215], v204 offset:0x1a00
	ds_read_b64_tr_b16 v[216:217], v204 offset:0x1b00
	s_waitcnt lgkmcnt(8)
	s_waitcnt lgkmcnt(0)
	v_mfma_f32_32x32x16_bf16 v[80:95], v[168:171], v[116:119], v[80:95]
	v_mfma_f32_32x32x16_bf16 v[0:15], v[60:63], v[182:185], v[0:15]
	s_waitcnt lgkmcnt(0)
	v_mfma_f32_32x32x16_bf16 v[0:15], v[56:59], v[146:149], v[0:15]
	v_mfma_f32_32x32x16_bf16 v[0:15], v[52:55], v[186:189], v[0:15]
	v_mfma_f32_32x32x16_bf16 v[0:15], v[48:51], v[190:193], v[0:15]
	s_waitcnt lgkmcnt(0)
	s_cmp_lg_u32 s40, 0
	s_cbranch_scc0 .Lmla_nobar4
	s_barrier
.Lmla_nobar4:
	v_mfma_f32_32x32x16_bf16 v[16:31], v[60:63], v[206:209], v[16:31]
	s_waitcnt lgkmcnt(0)
	v_mfma_f32_32x32x16_bf16 v[16:31], v[56:59], v[150:153], v[16:31]
	v_mfma_f32_32x32x16_bf16 v[16:31], v[52:55], v[210:213], v[16:31]
	v_mfma_f32_32x32x16_bf16 v[16:31], v[48:51], v[214:217], v[16:31]
	s_cmp_lg_u64 s[44:45], 0
	s_cbranch_scc0 .Lmla_w1_tail
	s_waitcnt vmcnt(3)
	ds_write_b128 v196, v[120:123]
	ds_write_b128 v197, v[128:131] offset:26624
	s_cmp_lg_u32 s8, 0
	s_cbranch_scc0 .LBB0_975
	ds_write_b128 v238, v[124:127] offset:128

; __device__ __forceinline__ void pv_both_kp(f32x16& o0, f32x16& o1, int vb, bf16x8 pa0, bf16x8 pa1, bf16x8 pa2, bf16x8 pa3) {
;     ...
;     asm volatile("s_waitcnt lgkmcnt(8)" ::: "memory"); __builtin_amdgcn_sched_barrier(0);
;     ...
;     o0 = __builtin_amdgcn_mfma_f32_32x32x16_bf16(pa0, PK(l0, h0), o0, 0, 0, 0);
;     o0 = __builtin_amdgcn_mfma_f32_32x32x16_bf16(pa1, PK(l1, h1), o0, 0, 0, 0);
;     o0 = __builtin_amdgcn_mfma_f32_32x32x16_bf16(pa2, PK(l2, h2), o0, 0, 0, 0);
;     o0 = __builtin_amdgcn_mfma_f32_32x32x16_bf16(pa3, PK(l3, h3), o0, 0, 0, 0);
;     asm volatile("s_waitcnt lgkmcnt(0)" ::: "memory"); __builtin_amdgcn_sched_barrier(0);
;     o1 = __builtin_amdgcn_mfma_f32_32x32x16_bf16(pa0, PK(m0, n0), o1, 0, 0, 0);
;     o1 = __builtin_amdgcn_mfma_f32_32x32x16_bf16(pa1, PK(m1, n1), o1, 0, 0, 0);
;     o1 = __builtin_amdgcn_mfma_f32_32x32x16_bf16(pa2, PK(m2, n2), o1, 0, 0, 0);
;     o1 = __builtin_amdgcn_mfma_f32_32x32x16_bf16(pa3, PK(m3, n3), o1, 0, 0, 0);
; __device__ __forceinline__ void mla_unit2(const Params& P, unsigned char* lds, int h, int rb, int grp, bool dry = false) {
;     ...
;         mla_qkt_neg(p0, p1, negm, K1, qr, r32, hi);
;         pv_both_kp(o[0], o[1], vb0, pa0, pa1, pa2, pa3);
.LBB0_985:
	s_waitcnt lgkmcnt(1)
	v_mfma_f32_32x32x16_bf16 v[64:79], v[146:149], v[96:99], v[32:47]
	ds_read_b128 v[146:149], v157 offset:19968
	ds_read_b128 v[162:165], v157 offset:20000
	s_waitcnt lgkmcnt(1)
	v_mfma_f32_32x32x16_bf16 v[48:63], v[146:149], v[96:99], v[32:47]
	v_mfma_f32_32x32x16_bf16 v[64:79], v[150:153], v[100:103], v[64:79]
	ds_read_b128 v[146:149], v157 offset:13376
	ds_read_b128 v[150:153], v157 offset:13408
	s_waitcnt lgkmcnt(2)
	v_mfma_f32_32x32x16_bf16 v[48:63], v[162:165], v[100:103], v[48:63]
	s_waitcnt lgkmcnt(1)
	v_mfma_f32_32x32x16_bf16 v[64:79], v[146:149], v[104:107], v[64:79]
	ds_read_b128 v[146:149], v157 offset:20032
	ds_read_b128 v[162:165], v157 offset:20064
	s_waitcnt lgkmcnt(1)
	v_mfma_f32_32x32x16_bf16 v[48:63], v[146:149], v[104:107], v[48:63]
	v_mfma_f32_32x32x16_bf16 v[64:79], v[150:153], v[108:111], v[64:79]
	ds_read_b128 v[146:149], v157 offset:13440
	ds_read_b128 v[150:153], v157 offset:13472
	s_waitcnt lgkmcnt(2)
	v_mfma_f32_32x32x16_bf16 v[48:63], v[162:165], v[108:111], v[48:63]
	s_waitcnt lgkmcnt(1)
	v_mfma_f32_32x32x16_bf16 v[64:79], v[146:149], v[112:115], v[64:79]
	ds_read_b128 v[146:149], v157 offset:20096
	ds_read_b128 v[162:165], v157 offset:20128
	ds_read_b64_tr_b16 v[168:169], v199 offset:0
	ds_read_b64_tr_b16 v[170:171], v199 offset:0x100
	s_waitcnt lgkmcnt(1)
	v_mfma_f32_32x32x16_bf16 v[48:63], v[146:149], v[112:115], v[48:63]
	ds_read_b64_tr_b16 v[146:147], v199 offset:0x800
	ds_read_b64_tr_b16 v[148:149], v199 offset:0x900
	ds_read_b64_tr_b16 v[182:183], v199 offset:0x1000
	ds_read_b64_tr_b16 v[184:185], v199 offset:0x1100
	ds_read_b64_tr_b16 v[186:187], v199 offset:0x1800
	ds_read_b64_tr_b16 v[188:189], v199 offset:0x1900
	ds_read_b64_tr_b16 v[190:191], v199 offset:0x200
	ds_read_b64_tr_b16 v[192:193], v199 offset:0x300
	v_mfma_f32_32x32x16_bf16 v[64:79], v[150:153], v[116:119], v[64:79]
	ds_read_b64_tr_b16 v[150:151], v199 offset:0xa00
	ds_read_b64_tr_b16 v[152:153], v199 offset:0xb00
	ds_read_b64_tr_b16 v[208:209], v199 offset:0x1200
	ds_read_b64_tr_b16 v[210:211], v199 offset:0x1300
	ds_read_b64_tr_b16 v[212:213], v199 offset:0x1a00
	ds_read_b64_tr_b16 v[214:215], v199 offset:0x1b00
	s_waitcnt lgkmcnt(8)
	s_waitcnt lgkmcnt(0)
	v_mfma_f32_32x32x16_bf16 v[48:63], v[162:165], v[116:119], v[48:63]
	v_mfma_f32_32x32x16_bf16 v[0:15], v[92:95], v[168:171], v[0:15]
	s_waitcnt lgkmcnt(0)
	v_mfma_f32_32x32x16_bf16 v[0:15], v[88:91], v[146:149], v[0:15]
	v_mfma_f32_32x32x16_bf16 v[0:15], v[84:87], v[182:185], v[0:15]
	v_mfma_f32_32x32x16_bf16 v[0:15], v[80:83], v[186:189], v[0:15]
	s_waitcnt lgkmcnt(0)
	s_cmp_lg_u32 s40, 0
	s_cbranch_scc0 .Lmla_nobar6
	s_barrier
.Lmla_nobar6:
	v_mfma_f32_32x32x16_bf16 v[16:31], v[92:95], v[190:193], v[16:31]
	s_waitcnt lgkmcnt(0)
	v_mfma_f32_32x32x16_bf16 v[16:31], v[88:91], v[150:153], v[16:31]
	v_mfma_f32_32x32x16_bf16 v[16:31], v[84:87], v[208:211], v[16:31]
	v_mfma_f32_32x32x16_bf16 v[16:31], v[80:83], v[212:215], v[16:31]
	s_cmp_lt_i32 s47, s54
	s_cbranch_scc0 .Lmla_w2_tail
	s_waitcnt vmcnt(3)
	ds_write_b128 v200, v[136:139]
	ds_write_b128 v201, v[132:135] offset:26624
	s_cmp_lg_u32 s8, 0
	s_cbranch_scc0 .LBB0_991
	ds_write_b128 v239, v[140:143] offset:128
